# P0 x-to-bf16 stream loop hand-scheduled (16 loads in flight per row, v_cvt_pk_bf16, DPP wave sum) on top of the hand-scheduled P5
# baseline (speedup 1.0000x reference)
.LBB0_15:
	v_writelane_b32 v252, s6, 55
	s_nop 0
	v_readlane_b32 s0, v252, 0
	v_readlane_b32 s1, v252, 1
	s_lshl_b32 s0, s0, 3
	s_lshr_b32 s97, s1, 6
	s_add_i32 s0, s97, s0
	s_add_u32 s4, s86, 0x10000
	v_writelane_b32 v252, s0, 56
	s_addc_u32 s5, s87, 0
	s_nop 0
	v_writelane_b32 v252, s1, 57
	s_add_u32 s0, s86, 0x400000
	s_addc_u32 s1, s87, 0
	v_writelane_b32 v252, s0, 58
	s_nop 1
	v_writelane_b32 v252, s1, 59
	s_add_u32 s0, s86, 0x1000000
	s_addc_u32 s1, s87, 0
	v_writelane_b32 v252, s0, 60
	s_nop 1
	v_writelane_b32 v252, s1, 61
	s_add_u32 s0, s86, 0x2600000
	s_addc_u32 s1, s87, 0
	v_writelane_b32 v252, s0, 62
	s_nop 1
	v_writelane_b32 v252, s1, 63
	s_add_u32 s0, s86, 0x9600000
	v_writelane_b32 v253, s0, 0
	s_addc_u32 s0, s87, 0
	v_writelane_b32 v253, s0, 1
	s_add_u32 s0, s86, 0x19800000
	v_writelane_b32 v253, s0, 2
	s_addc_u32 s0, s87, 0
	s_lshl_b32 s66, s33, 3
	s_add_u32 s94, s86, 0x200000
	s_addc_u32 s95, s87, 0
	v_writelane_b32 v253, s0, 3
	s_add_u32 s0, s86, 0x800000
	s_addc_u32 s1, s87, 0
	v_writelane_b32 v253, s0, 4
	s_nop 1
	v_writelane_b32 v253, s1, 5
	s_add_u32 s0, s86, 0x1400000
	s_addc_u32 s1, s87, 0
	v_writelane_b32 v253, s0, 6
	s_nop 1
	v_writelane_b32 v253, s1, 7
	s_add_u32 s0, s86, 0x4600000
	s_addc_u32 s1, s87, 0
	v_writelane_b32 v253, s0, 8
	s_nop 1
	v_writelane_b32 v253, s1, 9
	s_add_u32 s0, s86, 0x14200000
	s_addc_u32 s1, s87, 0
	v_writelane_b32 v253, s0, 10
	s_nop 1
	v_writelane_b32 v253, s1, 11
	s_add_u32 s0, s86, 0x24400000
	s_addc_u32 s1, s87, 0
	s_cmp_lt_i32 s56, 1
	v_writelane_b32 v253, s0, 12
	s_cselect_b64 s[6:7], -1, 0
	s_cmp_gt_i32 s56, 0
	v_writelane_b32 v253, s1, 13
	s_cselect_b64 s[0:1], -1, 0
	s_cmp_lt_i32 s57, 1
	s_cselect_b64 s[2:3], -1, 0
	s_or_b64 s[0:1], s[0:1], s[2:3]
	v_writelane_b32 v253, s56, 14
	s_and_b64 vcc, exec, s[0:1]
	s_nop 0
	v_writelane_b32 v253, s57, 15
	s_cbranch_vccnz .LBB0_34
	v_readlane_b32 s0, v252, 56
	v_and_b32_e32 v1, 63, v0
	s_cmpk_gt_i32 s0, 0x5fff
	v_bfe_u32 v122, v0, 3, 1
	v_readlane_b32 s1, v252, 57
	s_cbranch_scc1 .LBB0_23
	v_readlane_b32 s36, v252, 4
	v_readlane_b32 s37, v252, 5
	v_readlane_b32 s38, v252, 6
	v_readlane_b32 s39, v252, 7
	v_lshlrev_b32_e32 v2, 4, v1
	v_lshrrev_b32_e32 v3, 4, v1
	v_lshlrev_b32_e32 v3, 15, v3
	v_bfe_u32 v4, v1, 3, 1
	v_lshl_or_b32 v3, v4, 10, v3
	v_and_b32_e32 v4, 7, v1
	v_lshl_or_b32 v3, v4, 3, v3
	s_nop 1
.Lp0_row:
	s_add_i32 s1, s0, 0xffffc000
	s_cmpk_lt_u32 s0, 0x4000
	s_cselect_b32 s40, s36, s38
	s_cselect_b32 s41, s37, s39
	s_cselect_b32 s1, s0, s1
	s_lshl_b32 s1, s1, 14
	s_add_u32 s40, s40, s1
	s_addc_u32 s41, s41, 0
	s_add_u32 s42, s40, 0x1000
	s_addc_u32 s43, s41, 0
	s_add_u32 s44, s40, 0x2000
	s_addc_u32 s45, s41, 0
	s_add_u32 s46, s40, 0x3000
	s_addc_u32 s47, s41, 0
	global_load_dwordx4 v[8:11], v2, s[40:41]
	global_load_dwordx4 v[12:15], v2, s[40:41] offset:1024
	global_load_dwordx4 v[16:19], v2, s[40:41] offset:2048
	global_load_dwordx4 v[20:23], v2, s[40:41] offset:3072
	global_load_dwordx4 v[24:27], v2, s[42:43]
	global_load_dwordx4 v[28:31], v2, s[42:43] offset:1024
	global_load_dwordx4 v[32:35], v2, s[42:43] offset:2048
	global_load_dwordx4 v[36:39], v2, s[42:43] offset:3072
	global_load_dwordx4 v[40:43], v2, s[44:45]
	global_load_dwordx4 v[44:47], v2, s[44:45] offset:1024
	global_load_dwordx4 v[48:51], v2, s[44:45] offset:2048
	global_load_dwordx4 v[52:55], v2, s[44:45] offset:3072
	global_load_dwordx4 v[56:59], v2, s[46:47]
	global_load_dwordx4 v[60:63], v2, s[46:47] offset:1024
	global_load_dwordx4 v[64:67], v2, s[46:47] offset:2048
	global_load_dwordx4 v[68:71], v2, s[46:47] offset:3072
	s_lshr_b32 s1, s0, 8
	s_lshl_b32 s1, s1, 21
	s_bfe_u32 s2, s0, 0x10007
	s_lshl_b32 s2, s2, 14
	s_or_b32 s1, s1, s2
	s_bfe_u32 s2, s0, 0x30004
	s_lshl_b32 s2, s2, 11
	s_or_b32 s1, s1, s2
	s_and_b32 s2, s0, 15
	s_lshl_b32 s2, s2, 6
	s_or_b32 s1, s1, s2
	s_add_u32 s48, s34, s1
	s_addc_u32 s49, s35, 0
	s_bfe_u32 s2, s0, 0x10003
	s_lshl_b32 s2, s2, 5
	v_xor_b32_e32 v4, s2, v3
	s_lshl_b32 s1, s0, 3
	s_add_u32 s50, s4, s1
	s_addc_u32 s51, s5, 0
	v_mov_b32_e32 v6, 0
	v_mov_b32_e32 v7, 0
	s_waitcnt vmcnt(15)
	v_pk_mul_f32 v[72:73], v[8:9], v[8:9]
	v_pk_fma_f32 v[72:73], v[10:11], v[10:11], v[72:73]
	v_pk_add_f32 v[6:7], v[6:7], v[72:73]
	v_cvt_pk_bf16_f32 v74, v8, v9
	v_cvt_pk_bf16_f32 v75, v10, v11
	global_store_dwordx2 v4, v[74:75], s[48:49]
	s_waitcnt vmcnt(15)
	v_pk_mul_f32 v[76:77], v[12:13], v[12:13]
	v_pk_fma_f32 v[76:77], v[14:15], v[14:15], v[76:77]
	v_pk_add_f32 v[6:7], v[6:7], v[76:77]
	v_cvt_pk_bf16_f32 v78, v12, v13
	v_cvt_pk_bf16_f32 v79, v14, v15
	v_add_u32_e32 v5, 0x20000, v4
	global_store_dwordx2 v5, v[78:79], s[48:49]
	s_waitcnt vmcnt(15)
	v_pk_mul_f32 v[72:73], v[16:17], v[16:17]
	v_pk_fma_f32 v[72:73], v[18:19], v[18:19], v[72:73]
	v_pk_add_f32 v[6:7], v[6:7], v[72:73]
	v_cvt_pk_bf16_f32 v74, v16, v17
	v_cvt_pk_bf16_f32 v75, v18, v19
	v_add_u32_e32 v5, 0x40000, v4
	global_store_dwordx2 v5, v[74:75], s[48:49]
	s_waitcnt vmcnt(15)
	v_pk_mul_f32 v[76:77], v[20:21], v[20:21]
	v_pk_fma_f32 v[76:77], v[22:23], v[22:23], v[76:77]
	v_pk_add_f32 v[6:7], v[6:7], v[76:77]
	v_cvt_pk_bf16_f32 v78, v20, v21
	v_cvt_pk_bf16_f32 v79, v22, v23
	v_add_u32_e32 v5, 0x60000, v4
	global_store_dwordx2 v5, v[78:79], s[48:49]
	s_waitcnt vmcnt(15)
	v_pk_mul_f32 v[72:73], v[24:25], v[24:25]
	v_pk_fma_f32 v[72:73], v[26:27], v[26:27], v[72:73]
	v_pk_add_f32 v[6:7], v[6:7], v[72:73]
	v_cvt_pk_bf16_f32 v74, v24, v25
	v_cvt_pk_bf16_f32 v75, v26, v27
	v_add_u32_e32 v5, 0x80000, v4
	global_store_dwordx2 v5, v[74:75], s[48:49]
	s_waitcnt vmcnt(15)
	v_pk_mul_f32 v[76:77], v[28:29], v[28:29]
	v_pk_fma_f32 v[76:77], v[30:31], v[30:31], v[76:77]
	v_pk_add_f32 v[6:7], v[6:7], v[76:77]
	v_cvt_pk_bf16_f32 v78, v28, v29
	v_cvt_pk_bf16_f32 v79, v30, v31
	v_add_u32_e32 v5, 0xa0000, v4
	global_store_dwordx2 v5, v[78:79], s[48:49]
	s_waitcnt vmcnt(15)
	v_pk_mul_f32 v[72:73], v[32:33], v[32:33]
	v_pk_fma_f32 v[72:73], v[34:35], v[34:35], v[72:73]
	v_pk_add_f32 v[6:7], v[6:7], v[72:73]
	v_cvt_pk_bf16_f32 v74, v32, v33
	v_cvt_pk_bf16_f32 v75, v34, v35
	v_add_u32_e32 v5, 0xc0000, v4
	global_store_dwordx2 v5, v[74:75], s[48:49]
	s_waitcnt vmcnt(15)
	v_pk_mul_f32 v[76:77], v[36:37], v[36:37]
	v_pk_fma_f32 v[76:77], v[38:39], v[38:39], v[76:77]
	v_pk_add_f32 v[6:7], v[6:7], v[76:77]
	v_cvt_pk_bf16_f32 v78, v36, v37
	v_cvt_pk_bf16_f32 v79, v38, v39
	v_add_u32_e32 v5, 0xe0000, v4
	global_store_dwordx2 v5, v[78:79], s[48:49]
	s_waitcnt vmcnt(15)
	v_pk_mul_f32 v[72:73], v[40:41], v[40:41]
	v_pk_fma_f32 v[72:73], v[42:43], v[42:43], v[72:73]
	v_pk_add_f32 v[6:7], v[6:7], v[72:73]
	v_cvt_pk_bf16_f32 v74, v40, v41
	v_cvt_pk_bf16_f32 v75, v42, v43
	v_add_u32_e32 v5, 0x100000, v4
	global_store_dwordx2 v5, v[74:75], s[48:49]
	s_waitcnt vmcnt(15)
	v_pk_mul_f32 v[76:77], v[44:45], v[44:45]
	v_pk_fma_f32 v[76:77], v[46:47], v[46:47], v[76:77]
	v_pk_add_f32 v[6:7], v[6:7], v[76:77]
	v_cvt_pk_bf16_f32 v78, v44, v45
	v_cvt_pk_bf16_f32 v79, v46, v47
	v_add_u32_e32 v5, 0x120000, v4
	global_store_dwordx2 v5, v[78:79], s[48:49]
	s_waitcnt vmcnt(15)
	v_pk_mul_f32 v[72:73], v[48:49], v[48:49]
	v_pk_fma_f32 v[72:73], v[50:51], v[50:51], v[72:73]
	v_pk_add_f32 v[6:7], v[6:7], v[72:73]
	v_cvt_pk_bf16_f32 v74, v48, v49
	v_cvt_pk_bf16_f32 v75, v50, v51
	v_add_u32_e32 v5, 0x140000, v4
	global_store_dwordx2 v5, v[74:75], s[48:49]
	s_waitcnt vmcnt(15)
	v_pk_mul_f32 v[76:77], v[52:53], v[52:53]
	v_pk_fma_f32 v[76:77], v[54:55], v[54:55], v[76:77]
	v_pk_add_f32 v[6:7], v[6:7], v[76:77]
	v_cvt_pk_bf16_f32 v78, v52, v53
	v_cvt_pk_bf16_f32 v79, v54, v55
	v_add_u32_e32 v5, 0x160000, v4
	global_store_dwordx2 v5, v[78:79], s[48:49]
	s_waitcnt vmcnt(15)
	v_pk_mul_f32 v[72:73], v[56:57], v[56:57]
	v_pk_fma_f32 v[72:73], v[58:59], v[58:59], v[72:73]
	v_pk_add_f32 v[6:7], v[6:7], v[72:73]
	v_cvt_pk_bf16_f32 v74, v56, v57
	v_cvt_pk_bf16_f32 v75, v58, v59
	v_add_u32_e32 v5, 0x180000, v4
	global_store_dwordx2 v5, v[74:75], s[48:49]
	s_waitcnt vmcnt(15)
	v_pk_mul_f32 v[76:77], v[60:61], v[60:61]
	v_pk_fma_f32 v[76:77], v[62:63], v[62:63], v[76:77]
	v_pk_add_f32 v[6:7], v[6:7], v[76:77]
	v_cvt_pk_bf16_f32 v78, v60, v61
	v_cvt_pk_bf16_f32 v79, v62, v63
	v_add_u32_e32 v5, 0x1a0000, v4
	global_store_dwordx2 v5, v[78:79], s[48:49]
	s_waitcnt vmcnt(15)
	v_pk_mul_f32 v[72:73], v[64:65], v[64:65]
	v_pk_fma_f32 v[72:73], v[66:67], v[66:67], v[72:73]
	v_pk_add_f32 v[6:7], v[6:7], v[72:73]
	v_cvt_pk_bf16_f32 v74, v64, v65
	v_cvt_pk_bf16_f32 v75, v66, v67
	v_add_u32_e32 v5, 0x1c0000, v4
	global_store_dwordx2 v5, v[74:75], s[48:49]
	s_waitcnt vmcnt(15)
	v_pk_mul_f32 v[76:77], v[68:69], v[68:69]
	v_pk_fma_f32 v[76:77], v[70:71], v[70:71], v[76:77]
	v_pk_add_f32 v[6:7], v[6:7], v[76:77]
	v_cvt_pk_bf16_f32 v78, v68, v69
	v_cvt_pk_bf16_f32 v79, v70, v71
	v_add_u32_e32 v5, 0x1e0000, v4
	global_store_dwordx2 v5, v[78:79], s[48:49]
	v_add_f32_e32 v72, v6, v7
	s_nop 1
	v_add_f32_dpp v72, v72, v72 quad_perm:[1,0,3,2] row_mask:0xf bank_mask:0xf
	s_nop 1
	v_add_f32_dpp v72, v72, v72 quad_perm:[2,3,0,1] row_mask:0xf bank_mask:0xf
	s_nop 1
	v_add_f32_dpp v72, v72, v72 row_ror:4 row_mask:0xf bank_mask:0xf
	s_nop 1
	v_add_f32_dpp v72, v72, v72 row_ror:8 row_mask:0xf bank_mask:0xf
	s_nop 1
	v_readlane_b32 s1, v72, 0
	v_readlane_b32 s2, v72, 16
	v_readlane_b32 s3, v72, 32
	v_readlane_b32 s8, v72, 48
	s_nop 2
	v_mov_b32_e32 v73, s1
	v_add_f32_e32 v73, s2, v73
	v_add_f32_e32 v73, s3, v73
	v_add_f32_e32 v73, s8, v73
	v_mul_f32_e32 v73, 0x47800000, v73
	v_trunc_f32_e32 v73, v73
	v_mul_f32_e32 v74, 0x2f800000, v73
	v_floor_f32_e32 v75, v74
	v_fmac_f32_e32 v73, 0xcf800000, v75
	v_cvt_u32_f32_e32 v74, v73
	v_cvt_u32_f32_e32 v75, v75
	v_mov_b32_e32 v73, 0
	s_mov_b64 exec, 1
	global_store_dwordx2 v73, v[74:75], s[50:51]
	s_mov_b64 exec, -1
	s_add_i32 s0, s0, s66
	s_cmpk_lt_u32 s0, 0x6000
	s_cbranch_scc1 .Lp0_row
